# hg_item(false): next-chunk load block moved from after step 1 to the top of the chunk iteration (value words land in shadow regs v232-239, copied at the back-edge)
# speedup vs baseline: 1.0113x; 1.0050x over previous
; #define LAS __attribute__((address_space(3)))
; template <bool FULL, bool STORE = true>
; __device__ __forceinline__ void hg_item(const Prm& P, LAS unsigned char* lds, int item, int wave) {
;     ...
;         for (int g4 = 0; g4 < 4; ++g4) { const f32x4 d = *(const LAS f32x4*)(lds + HL_DC + (kb * 32 + 8 * g4 + 4 * lh) * 4);
; #pragma unroll
;             for (int i = 0; i < 2; ++i)
; #pragma unroll
;                 for (int j = 0; j < 4; ++j) S[i][4 * g4 + j] *= d[j]; }
; #pragma unroll
;         for (int ks = 0; ks < 4; ++ks) { const bf16x8 a = *(const LAS bf16x8*)(lds + HL_KDT + (kb * 32 + l31) * 144 + ks * 32 + lh * 16);
; #pragma unroll
;             for (int i = 0; i < 2; ++i) { const bf16x8 bb = *(const LAS bf16x8*)(lds + HL_IVT + ((vb0 + i) * 32 + l31) * 144 + ks * 32 + lh * 16); S[i] = __builtin_amdgcn_mfma_f32_32x32x16_bf16(a, bb, S[i], 0, 0, 0); } }
.LBB0_701:
	v_add_u32_e32 v33, s48, v67
	s_waitcnt lgkmcnt(0)
	s_barrier
	ds_read_b128 v[76:79], v33
	ds_read_b128 v[80:83], v33 offset:32
	s_add_u32 s34, s34, 0x20000
	s_addc_u32 s35, s35, 0
	s_add_u32 s26, s26, 0x10000
	s_waitcnt lgkmcnt(1)
	v_pk_mul_f32 v[16:17], v[16:17], v[76:77]
	v_pk_mul_f32 v[18:19], v[18:19], v[78:79]
	v_pk_mul_f32 v[0:1], v[0:1], v[76:77]
	v_pk_mul_f32 v[2:3], v[2:3], v[78:79]
	ds_read_b128 v[76:79], v33 offset:64
	ds_read_b128 v[84:87], v33 offset:96
	ds_read_b128 v[88:91], v73 offset:52224
	ds_read_b128 v[92:95], v74
	s_waitcnt lgkmcnt(4)
	v_pk_mul_f32 v[20:21], v[20:21], v[80:81]
	v_pk_mul_f32 v[22:23], v[22:23], v[82:83]
	v_pk_mul_f32 v[4:5], v[4:5], v[80:81]
	s_waitcnt lgkmcnt(3)
	v_pk_mul_f32 v[24:25], v[24:25], v[76:77]
	v_pk_mul_f32 v[26:27], v[26:27], v[78:79]
	s_waitcnt lgkmcnt(2)
	v_pk_mul_f32 v[28:29], v[28:29], v[84:85]
	v_pk_mul_f32 v[30:31], v[30:31], v[86:87]
	ds_read_b128 v[96:99], v73 offset:52256
	ds_read_b128 v[100:103], v74 offset:32
	v_pk_mul_f32 v[6:7], v[6:7], v[82:83]
	ds_read_b128 v[80:83], v74 offset:4608
	s_waitcnt lgkmcnt(3)
	v_mfma_f32_32x32x16_bf16 v[16:31], v[88:91], v[92:95], v[16:31]
	v_mul_f32_e64 v8, v8, v76
	v_mul_f32_e64 v9, v9, v77
	v_mul_f32_e64 v10, v10, v78
	v_mul_f32_e64 v11, v11, v79
	v_mul_f32_e64 v12, v12, v84
	v_mul_f32_e64 v13, v13, v85
	v_pk_mul_f32 v[14:15], v[14:15], v[86:87]
	ds_read_b128 v[76:79], v74 offset:4640
	s_addc_u32 s38, s38, 0
	s_cmp_eq_u32 s34, 0x200000
	s_waitcnt lgkmcnt(1)
	v_mfma_f32_32x32x16_bf16 v[0:15], v[88:91], v[80:83], v[0:15]
	v_mfma_f32_32x32x16_bf16 v[16:31], v[96:99], v[100:103], v[16:31]
	s_waitcnt lgkmcnt(0)
	v_mfma_f32_32x32x16_bf16 v[0:15], v[96:99], v[76:79], v[0:15]
	ds_read_b128 v[76:79], v73 offset:52288
	ds_read_b128 v[80:83], v74 offset:64
	ds_read_b128 v[84:87], v73 offset:52320
	ds_read_b128 v[88:91], v74 offset:96
	s_waitcnt lgkmcnt(2)
	v_mfma_f32_32x32x16_bf16 v[16:31], v[76:79], v[80:83], v[16:31]
	ds_read_b128 v[80:83], v74 offset:4672
	ds_read_b128 v[92:95], v74 offset:4704
	s_waitcnt lgkmcnt(1)
	v_mfma_f32_32x32x16_bf16 v[0:15], v[76:79], v[80:83], v[0:15]
	v_mfma_f32_32x32x16_bf16 v[16:31], v[84:87], v[88:91], v[16:31]
	s_waitcnt lgkmcnt(0)
	v_mfma_f32_32x32x16_bf16 v[0:15], v[84:87], v[92:95], v[0:15]
	s_cbranch_scc1 .LBB0_706
	s_waitcnt vmcnt(0)
	v_cvt_f32_f16_e32 v46, v240
	v_cvt_f32_f16_sdwa v47, v240 dst_sel:DWORD dst_unused:UNUSED_PAD src0_sel:WORD_1
	v_cvt_f32_f16_e32 v48, v241
	v_cvt_f32_f16_sdwa v49, v241 dst_sel:DWORD dst_unused:UNUSED_PAD src0_sel:WORD_1
	v_cvt_f32_f16_e32 v50, v242
	v_cvt_f32_f16_sdwa v51, v242 dst_sel:DWORD dst_unused:UNUSED_PAD src0_sel:WORD_1
	v_cvt_f32_f16_e32 v52, v243
	v_cvt_f32_f16_sdwa v53, v243 dst_sel:DWORD dst_unused:UNUSED_PAD src0_sel:WORD_1
	v_cvt_f32_f16_e32 v54, v244
	v_cvt_f32_f16_sdwa v55, v244 dst_sel:DWORD dst_unused:UNUSED_PAD src0_sel:WORD_1
	v_cvt_f32_f16_e32 v56, v245
	v_cvt_f32_f16_sdwa v57, v245 dst_sel:DWORD dst_unused:UNUSED_PAD src0_sel:WORD_1
	v_cvt_f32_f16_e32 v58, v246
	v_cvt_f32_f16_sdwa v59, v246 dst_sel:DWORD dst_unused:UNUSED_PAD src0_sel:WORD_1
	v_cvt_f32_f16_e32 v60, v247
	v_cvt_f32_f16_sdwa v61, v247 dst_sel:DWORD dst_unused:UNUSED_PAD src0_sel:WORD_1
	v_mov_b32_e32 v37, v232
	v_mov_b32_e32 v65, v233
	v_mov_b32_e32 v68, v234
	v_mov_b32_e32 v69, v235
	v_mov_b32_e32 v70, v236
	v_mov_b32_e32 v71, v237
	v_mov_b32_e32 v72, v238
	v_mov_b32_e32 v75, v239
	s_nop 0
.LBB0_702:
	s_cmp_eq_u32 s34, 0x1e0000
	s_cbranch_scc1 .Lhgf_noload
	v_lshl_add_u64 v[224:225], v[42:43], 0, s[34:35]
	global_load_dword v240, v[224:225], off
	v_lshl_add_u64 v[224:225], v[44:45], 0, s[34:35]
	s_or_b32 s36, s26, 0x400
	s_mov_b32 s37, s38
	global_load_dword v232, v[224:225], off
	v_lshl_add_u64 v[224:225], s[36:37], 0, v[38:39]
	v_lshlrev_b64 v[224:225], 1, v[224:225]
	v_lshl_add_u64 v[226:227], s[70:71], 0, v[224:225]
	v_lshl_add_u64 v[224:225], s[24:25], 0, v[224:225]
	s_or_b32 s36, s26, 0x800
	global_load_dword v233, v[224:225], off
	v_lshl_add_u64 v[224:225], s[36:37], 0, v[38:39]
	v_lshlrev_b64 v[224:225], 1, v[224:225]
	global_load_dword v241, v[226:227], off
	v_lshl_add_u64 v[226:227], s[70:71], 0, v[224:225]
	v_lshl_add_u64 v[224:225], s[24:25], 0, v[224:225]
	s_or_b32 s36, s26, 0xc00
	global_load_dword v234, v[224:225], off
	v_lshl_add_u64 v[224:225], s[36:37], 0, v[38:39]
	v_lshlrev_b64 v[224:225], 1, v[224:225]
	global_load_dword v242, v[226:227], off
	v_lshl_add_u64 v[226:227], s[70:71], 0, v[224:225]
	v_lshl_add_u64 v[224:225], s[24:25], 0, v[224:225]
	s_or_b32 s36, s26, 0x1000
	global_load_dword v235, v[224:225], off
	v_lshl_add_u64 v[224:225], s[36:37], 0, v[38:39]
	v_lshlrev_b64 v[224:225], 1, v[224:225]
	global_load_dword v243, v[226:227], off
	v_lshl_add_u64 v[226:227], s[70:71], 0, v[224:225]
	v_lshl_add_u64 v[224:225], s[24:25], 0, v[224:225]
	s_or_b32 s36, s26, 0x1400
	global_load_dword v236, v[224:225], off
	v_lshl_add_u64 v[224:225], s[36:37], 0, v[38:39]
	v_lshlrev_b64 v[224:225], 1, v[224:225]
	global_load_dword v244, v[226:227], off
	v_lshl_add_u64 v[226:227], s[70:71], 0, v[224:225]
	s_or_b32 s36, s26, 0x1800
	global_load_dword v245, v[226:227], off
	v_lshl_add_u64 v[226:227], s[36:37], 0, v[38:39]
	v_lshlrev_b64 v[226:227], 1, v[226:227]
	v_lshl_add_u64 v[228:229], s[70:71], 0, v[226:227]
	s_or_b32 s36, s26, 0x1c00
	global_load_dword v246, v[228:229], off
	v_lshl_add_u64 v[228:229], s[36:37], 0, v[38:39]
	v_lshlrev_b64 v[228:229], 1, v[228:229]
	v_lshl_add_u64 v[230:231], s[70:71], 0, v[228:229]
	v_lshl_add_u64 v[224:225], s[24:25], 0, v[224:225]
	global_load_dword v247, v[230:231], off
	global_load_dword v237, v[224:225], off
	v_lshl_add_u64 v[224:225], s[24:25], 0, v[226:227]
	global_load_dword v238, v[224:225], off
	v_lshl_add_u64 v[224:225], s[24:25], 0, v[228:229]
	global_load_dword v239, v[224:225], off
; #define LAS __attribute__((address_space(3)))
; template <bool FULL, bool STORE = true>
; __device__ __forceinline__ void hg_item(const Prm& P, LAS unsigned char* lds, int item, int wave) {
;     ...
;         for (int i = 0; i < 8; ++i) { f0[i] = __expf(c0[i]); f1[i] = __expf(c1[i]); ka[i] = 1.0f - f0[i]; kc[i] = 1.0f - f1[i]; t0 += c0[i]; t1 += c1[i]; }
;         *(LAS f32x2*)(lds + HL_TOT + (tg * 128 + k2) * 4) = (f32x2){t0, t1};
;         __syncthreads();
;         float off0 = 0.f, off1 = 0.f, bm0 = 0.f, bm1 = 0.f, bl0 = 0.f, bl1 = 0.f;
; #pragma unroll
;         for (int g8 = 0; g8 < 8; ++g8) { const f32x2 t2 = *(const LAS f32x2*)(lds + HL_TOT + (g8 * 128 + k2) * 4); if (g8 < tg) { off0 += t2.x; off1 += t2.y; } if (g8 < 4) { bm0 += t2.x; bm1 += t2.y; } bl0 += t2.x; bl1 += t2.y; }
;         {
;             float kd0[8], kd1[8], iv0[8], iv1[8];
;             float e0 = __expf(off0 + c0[0] - bm0), e1 = __expf(off1 + c1[0] - bm1);
;             const float ebm0 = __expf(bm0), ebm1 = __expf(bm1), ebl0 = __expf(bl0 - bm0), ebl1 = __expf(bl1 - bm1);
; #pragma unroll
;             for (int i = 0; i < 8; ++i) { if (i) { e0 *= f0[i]; e1 *= f1[i]; }
;                 const float r0 = __builtin_amdgcn_rcpf(e0), r1 = __builtin_amdgcn_rcpf(e1);
;                 kd0[i] = ka[i] * r0 * ebl0; kd1[i] = kc[i] * r1 * ebl1; iv0[i] = bflo(ivw[i]); iv1[i] = bfhi(ivw[i]);
.Lhgf_noload:
	v_mul_f32_e32 v33, 0x3fb8aa3b, v48
	v_exp_f32_e32 v93, v33
	v_mul_f32_e32 v33, 0x3fb8aa3b, v49
	v_exp_f32_e32 v95, v33
	v_mul_f32_e32 v33, 0x3fb8aa3b, v50
	v_exp_f32_e32 v96, v33
	v_mul_f32_e32 v33, 0x3fb8aa3b, v51
	v_exp_f32_e32 v98, v33
	v_mul_f32_e32 v33, 0x3fb8aa3b, v52
	v_exp_f32_e32 v97, v33
	v_mul_f32_e32 v33, 0x3fb8aa3b, v53
	v_pk_add_f32 v[62:63], v[46:47], 0 op_sel_hi:[1,0]
	v_exp_f32_e32 v99, v33
	v_mul_f32_e32 v33, 0x3fb8aa3b, v54
	v_exp_f32_e32 v100, v33
	v_mul_f32_e32 v33, 0x3fb8aa3b, v55
	v_pk_add_f32 v[62:63], v[62:63], v[48:49]
	v_exp_f32_e32 v102, v33
	v_mul_f32_e32 v33, 0x3fb8aa3b, v56
	v_pk_add_f32 v[62:63], v[62:63], v[50:51]
	v_exp_f32_e32 v101, v33
	v_mul_f32_e32 v33, 0x3fb8aa3b, v57
	v_pk_add_f32 v[62:63], v[62:63], v[52:53]
	v_exp_f32_e32 v103, v33
	v_mul_f32_e32 v33, 0x3fb8aa3b, v58
	v_pk_add_f32 v[62:63], v[62:63], v[54:55]
	v_exp_f32_e32 v104, v33
	v_mul_f32_e32 v33, 0x3fb8aa3b, v59
	v_pk_add_f32 v[62:63], v[62:63], v[56:57]
	v_exp_f32_e32 v106, v33
	v_mul_f32_e32 v33, 0x3fb8aa3b, v60
	v_pk_add_f32 v[62:63], v[62:63], v[58:59]
	v_exp_f32_e32 v105, v33
	v_pk_add_f32 v[62:63], v[62:63], v[60:61]
	v_add_u32_e32 v33, s45, v64
	ds_write_b64 v33, v[62:63]
	v_add_u32_e32 v33, 0, v64
	v_add_u32_e32 v62, 0x20800, v33
	s_waitcnt lgkmcnt(0)
	s_barrier
	ds_read2st64_b64 v[76:79], v62 offset1:1
	v_mul_f32_e32 v80, 0x3fb8aa3b, v61
	v_exp_f32_e32 v107, v80
	ds_read2st64_b64 v[80:83], v62 offset0:2 offset1:3
	ds_read2st64_b64 v[84:87], v62 offset0:4 offset1:5
	ds_read2st64_b64 v[88:91], v62 offset0:6 offset1:7
	v_lshlrev_b32_e32 v108, 16, v37
	s_waitcnt lgkmcnt(3)
	v_pk_add_f32 v[62:63], v[76:77], 0 op_sel_hi:[1,0]
	v_lshlrev_b32_e32 v110, 16, v65
	v_cndmask_b32_e64 v77, v62, 0, s[88:89]
	v_cndmask_b32_e64 v76, v63, 0, s[88:89]
	v_add_f32_e32 v92, v78, v77
	v_add_f32_e32 v94, v79, v76
	v_cndmask_b32_e64 v77, v77, v92, s[4:5]
	v_cndmask_b32_e64 v76, v76, v94, s[4:5]
	v_pk_add_f32 v[62:63], v[62:63], v[78:79]
	s_waitcnt lgkmcnt(2)
	v_add_f32_e32 v78, v80, v77
	v_add_f32_e32 v79, v81, v76
	v_cndmask_b32_e64 v77, v77, v78, s[6:7]
	v_cndmask_b32_e64 v76, v76, v79, s[6:7]
	v_add_f32_e32 v78, v82, v77
	v_pk_add_f32 v[62:63], v[62:63], v[80:81]
	v_add_f32_e32 v79, v83, v76
	v_cndmask_b32_e64 v78, v77, v78, s[8:9]
	v_cndmask_b32_e64 v79, v76, v79, s[8:9]
	v_pk_add_f32 v[76:77], v[62:63], v[82:83]
	s_waitcnt lgkmcnt(1)
	v_add_f32_e32 v62, v84, v78
	v_cndmask_b32_e64 v78, v78, v62, s[10:11]
	v_add_f32_e32 v80, v86, v78
	v_add_f32_e32 v63, v85, v79
	v_cndmask_b32_e64 v78, v78, v80, s[12:13]
	v_cndmask_b32_e64 v79, v79, v63, s[10:11]
	s_waitcnt lgkmcnt(0)
	v_add_f32_e32 v80, v88, v78
	v_add_f32_e32 v81, v87, v79
	v_cndmask_b32_e64 v78, v78, v80, s[14:15]
	v_cndmask_b32_e64 v79, v79, v81, s[12:13]
	v_add_f32_e32 v80, v90, v78
	v_add_f32_e32 v81, v89, v79
	v_cndmask_b32_e64 v78, v78, v80, s[16:17]
	v_pk_add_f32 v[62:63], v[76:77], v[84:85]
	v_cndmask_b32_e64 v79, v79, v81, s[14:15]
	v_add_f32_e32 v78, v46, v78
	v_pk_add_f32 v[62:63], v[62:63], v[86:87]
	v_add_f32_e32 v81, v91, v79
	v_sub_f32_e32 v78, v78, v76
	v_pk_add_f32 v[62:63], v[62:63], v[88:89]
	v_cndmask_b32_e64 v79, v79, v81, s[16:17]
	v_mul_f32_e32 v78, 0x3fb8aa3b, v78
	v_pk_add_f32 v[62:63], v[62:63], v[90:91]
	v_exp_f32_e32 v81, v78
	v_add_f32_e32 v78, v47, v79
	v_sub_f32_e32 v78, v78, v77
	v_pk_add_f32 v[76:77], v[62:63], v[76:77] neg_lo:[0,1] neg_hi:[0,1]
	v_mul_f32_e32 v78, 0x3fb8aa3b, v78
	v_mul_f32_e32 v77, 0x3fb8aa3b, v77
	v_exp_f32_e32 v79, v78
	v_exp_f32_e32 v78, v77
	v_mul_f32_e32 v77, 0x3fb8aa3b, v47
	v_exp_f32_e32 v94, v77
	v_mul_f32_e32 v77, 0x3fb8aa3b, v46
	v_exp_f32_e32 v92, v77
	v_mul_f32_e32 v77, v93, v81
	v_mul_f32_e32 v76, 0x3fb8aa3b, v76
	v_rcp_f32_e32 v80, v81
	v_rcp_f32_e32 v81, v77
	v_exp_f32_e32 v76, v76
	v_rcp_f32_e32 v82, v79
	v_mul_f32_e32 v79, v95, v79
	v_rcp_f32_e32 v83, v79
	v_pk_add_f32 v[84:85], v[92:93], 1.0 op_sel_hi:[1,0] neg_lo:[1,0] neg_hi:[1,0]
	v_pk_add_f32 v[88:89], v[96:97], 1.0 op_sel_hi:[1,0] neg_lo:[1,0] neg_hi:[1,0]
	v_pk_mul_f32 v[80:81], v[84:85], v[80:81]
	v_pk_add_f32 v[84:85], v[94:95], 1.0 op_sel_hi:[1,0] neg_lo:[1,0] neg_hi:[1,0]
	v_pk_mul_f32 v[80:81], v[76:77], v[80:81] op_sel_hi:[0,1]
	v_mul_f32_e32 v77, v96, v77
	v_pk_mul_f32 v[82:83], v[84:85], v[82:83]
	v_rcp_f32_e32 v84, v77
	v_mul_f32_e32 v77, v97, v77
	v_pk_mul_f32 v[82:83], v[78:79], v[82:83] op_sel_hi:[0,1]
	v_mul_f32_e32 v79, v98, v79
	v_rcp_f32_e32 v85, v77
	v_rcp_f32_e32 v86, v79
	v_mul_f32_e32 v79, v99, v79
	v_rcp_f32_e32 v87, v79
	v_pk_mul_f32 v[84:85], v[88:89], v[84:85]
	v_pk_add_f32 v[88:89], v[98:99], 1.0 op_sel_hi:[1,0] neg_lo:[1,0] neg_hi:[1,0]
	v_pk_mul_f32 v[84:85], v[76:77], v[84:85] op_sel_hi:[0,1]
	v_mul_f32_e32 v77, v100, v77
	v_pk_mul_f32 v[86:87], v[88:89], v[86:87]
	v_rcp_f32_e32 v88, v77
	v_mul_f32_e32 v77, v101, v77
	v_pk_mul_f32 v[86:87], v[78:79], v[86:87] op_sel_hi:[0,1]
	v_mul_f32_e32 v79, v102, v79
	v_rcp_f32_e32 v89, v77
; #define LAS __attribute__((address_space(3)))
; __device__ __forceinline__ unsigned pk2(float lo, float hi) { typedef float f2v __attribute__((ext_vector_type(2))); typedef __bf16 b2v __attribute__((ext_vector_type(2))); const f2v v = {lo, hi}; const b2v b = __builtin_convertvector(v, b2v); return __builtin_bit_cast(unsigned, b); }
; __device__ __forceinline__ u32x4 pack8(const float (&f)[8]) { u32x4 w; w.x = pk2(f[0], f[1]); w.y = pk2(f[2], f[3]); w.z = pk2(f[4], f[5]); w.w = pk2(f[6], f[7]); return w; }
; #define lane lane_id()
; template <bool FULL, bool STORE = true>
; __device__ __forceinline__ void hg_item(const Prm& P, LAS unsigned char* lds, int item, int wave) {
;     ...
;             for (int i = 0; i < 8; ++i) { if (i) { e0 *= f0[i]; e1 *= f1[i]; }
;                 const float r0 = __builtin_amdgcn_rcpf(e0), r1 = __builtin_amdgcn_rcpf(e1);
;                 kd0[i] = ka[i] * r0 * ebl0; kd1[i] = kc[i] * r1 * ebl1; iv0[i] = bflo(ivw[i]); iv1[i] = bfhi(ivw[i]);
;                 if (FULL) { const float qa = bflo(qw[i]), qc = bfhi(qw[i]); const int t = tg * 8 + i;
;                     *(LAS unsigned*)(lds + HL_QM + t * 272 + k2 * 2) = pk2(qa * e0, qc * e1);
;                     *(LAS unsigned*)(lds + HL_KM + t * 272 + k2 * 2) = pk2(ka[i] * r0, kc[i] * r1);
;                     *(LAS unsigned*)(lds + HL_QD + t * 272 + k2 * 2) = pk2(qa * e0 * ebm0, qc * e1 * ebm1); } }
;             *(LAS u32x4*)(lds + HL_KDT + k2 * 144 + tg * 16) = pack8(kd0); *(LAS u32x4*)(lds + HL_KDT + (k2 + 1) * 144 + tg * 16) = pack8(kd1);
;             *(LAS u32x4*)(lds + HL_IVT + k2 * 144 + tg * 16) = pack8(iv0); *(LAS u32x4*)(lds + HL_IVT + (k2 + 1) * 144 + tg * 16) = pack8(iv1);
;             if (tg == 0) { *(LAS f32x2*)(lds + HL_DC + k2 * 4) = (f32x2){__expf(bl0), __expf(bl1)}; sumlog0 += bl0; sumlog1 += bl1; }
;     ...
;     if (!FULL) {
; #pragma unroll
;         for (int i = 0; i < 2; ++i)
; #pragma unroll
;             for (int r = 0; r < 16; ++r) AGG[(size_t)((item * 8 + wave) * 2 + i) * 1024 + r * 64 + lane] = S[i][r];
;         if (tg == 0) *(f32x2*)(DEC + item * 128 + k2) = (f32x2){__expf(sumlog0), __expf(sumlog1)};
	v_rcp_f32_e32 v90, v79
	v_mul_f32_e32 v79, v103, v79
	v_rcp_f32_e32 v91, v79
	v_pk_add_f32 v[92:93], v[100:101], 1.0 op_sel_hi:[1,0] neg_lo:[1,0] neg_hi:[1,0]
	v_pk_add_f32 v[96:97], v[104:105], 1.0 op_sel_hi:[1,0] neg_lo:[1,0] neg_hi:[1,0]
	v_pk_mul_f32 v[88:89], v[92:93], v[88:89]
	v_pk_add_f32 v[92:93], v[102:103], 1.0 op_sel_hi:[1,0] neg_lo:[1,0] neg_hi:[1,0]
	v_pk_mul_f32 v[88:89], v[76:77], v[88:89] op_sel_hi:[0,1]
	v_mul_f32_e32 v77, v104, v77
	v_pk_mul_f32 v[90:91], v[92:93], v[90:91]
	v_rcp_f32_e32 v92, v77
	v_mul_f32_e32 v77, v105, v77
	v_pk_mul_f32 v[90:91], v[78:79], v[90:91] op_sel_hi:[0,1]
	v_mul_f32_e32 v79, v106, v79
	v_rcp_f32_e32 v93, v77
	v_mul_f32_e32 v77, v107, v79
	v_rcp_f32_e32 v94, v79
	v_rcp_f32_e32 v95, v77
	v_pk_mul_f32 v[92:93], v[96:97], v[92:93]
	v_lshlrev_b32_e32 v112, 16, v68
	v_pk_mul_f32 v[92:93], v[76:77], v[92:93] op_sel_hi:[0,1]
	v_pk_add_f32 v[76:77], v[106:107], 1.0 op_sel_hi:[1,0] neg_lo:[1,0] neg_hi:[1,0]
	v_lshlrev_b32_e32 v98, 16, v69
	v_pk_mul_f32 v[76:77], v[76:77], v[94:95]
	v_lshlrev_b32_e32 v114, 16, v70
	v_pk_mul_f32 v[94:95], v[78:79], v[76:77] op_sel_hi:[0,1]
	v_cvt_pk_bf16_f32 v76, v80, v81
	v_cvt_pk_bf16_f32 v77, v84, v85
	v_cvt_pk_bf16_f32 v78, v88, v89
	v_cvt_pk_bf16_f32 v79, v92, v93
	v_add_u32_e32 v80, s46, v66
	v_lshlrev_b32_e32 v100, 16, v71
	v_lshlrev_b32_e32 v102, 16, v72
	v_lshlrev_b32_e32 v96, 16, v75
	ds_write_b128 v80, v[76:79] offset:52224
	v_cvt_pk_bf16_f32 v76, v82, v83
	v_cvt_pk_bf16_f32 v77, v86, v87
	v_cvt_pk_bf16_f32 v78, v90, v91
	v_cvt_pk_bf16_f32 v79, v94, v95
	v_and_b32_e32 v109, 0xffff0000, v37
	v_and_b32_e32 v111, 0xffff0000, v65
	v_and_b32_e32 v113, 0xffff0000, v68
	v_and_b32_e32 v99, 0xffff0000, v69
	v_and_b32_e32 v115, 0xffff0000, v70
	v_and_b32_e32 v101, 0xffff0000, v71
	v_and_b32_e32 v103, 0xffff0000, v72
	v_and_b32_e32 v97, 0xffff0000, v75
	ds_write_b128 v80, v[76:79] offset:52368
	v_cvt_pk_bf16_f32 v76, v108, v110
	v_cvt_pk_bf16_f32 v77, v112, v98
	v_cvt_pk_bf16_f32 v78, v114, v100
	v_cvt_pk_bf16_f32 v79, v102, v96
	v_add_u32_e32 v80, s47, v66
	ds_write_b128 v80, v[76:79]
	v_cvt_pk_bf16_f32 v76, v109, v111
	v_cvt_pk_bf16_f32 v77, v113, v99
	v_cvt_pk_bf16_f32 v78, v115, v101
	v_cvt_pk_bf16_f32 v79, v103, v97
	s_and_b64 vcc, exec, s[0:1]
	ds_write_b128 v80, v[76:79] offset:144
	s_cbranch_vccnz .LBB0_704
	v_mul_f32_e32 v76, 0x3fb8aa3b, v62
	v_mul_f32_e32 v77, 0x3fb8aa3b, v63
	v_exp_f32_e32 v76, v76
	v_exp_f32_e32 v77, v77
	v_pk_add_f32 v[40:41], v[40:41], v[62:63]
	v_add_u32_e32 v33, 0x21800, v33
	ds_write_b64 v33, v[76:77]
.LBB0_704:
	s_branch .LBB0_701
.LBB0_706:
	s_add_i32 s34, s66, s2
	s_ashr_i32 s35, s34, 31
	v_ashrrev_i32_e32 v37, 31, v36
	s_lshl_b64 s[36:37], s[34:35], 12
	s_or_b32 s34, s34, 1
	v_lshl_add_u64 v[36:37], v[36:37], 2, s[22:23]
	s_ashr_i32 s35, s34, 31
	v_lshl_add_u64 v[38:39], v[36:37], 0, s[36:37]
	s_lshl_b64 s[34:35], s[34:35], 12
	global_store_dword v[38:39], v16, off
	global_store_dword v[38:39], v17, off offset:256
	global_store_dword v[38:39], v18, off offset:512
	global_store_dword v[38:39], v19, off offset:768
	global_store_dword v[38:39], v20, off offset:1024
	global_store_dword v[38:39], v21, off offset:1280
	global_store_dword v[38:39], v22, off offset:1536
	global_store_dword v[38:39], v23, off offset:1792
	global_store_dword v[38:39], v24, off offset:2048
	global_store_dword v[38:39], v25, off offset:2304
	global_store_dword v[38:39], v26, off offset:2560
	global_store_dword v[38:39], v27, off offset:2816
	global_store_dword v[38:39], v28, off offset:3072
	global_store_dword v[38:39], v29, off offset:3328
	global_store_dword v[38:39], v30, off offset:3584
	global_store_dword v[38:39], v31, off offset:3840
	v_lshl_add_u64 v[16:17], v[36:37], 0, s[34:35]
	s_and_b64 vcc, exec, s[88:89]
	global_store_dword v[16:17], v0, off
	global_store_dword v[16:17], v1, off offset:256
	global_store_dword v[16:17], v2, off offset:512
	global_store_dword v[16:17], v3, off offset:768
	global_store_dword v[16:17], v4, off offset:1024
	global_store_dword v[16:17], v5, off offset:1280
	global_store_dword v[16:17], v6, off offset:1536
	global_store_dword v[16:17], v7, off offset:1792
	global_store_dword v[16:17], v8, off offset:2048
	global_store_dword v[16:17], v9, off offset:2304
	global_store_dword v[16:17], v10, off offset:2560
	global_store_dword v[16:17], v11, off offset:2816
	global_store_dword v[16:17], v12, off offset:3072
	global_store_dword v[16:17], v13, off offset:3328
	global_store_dword v[16:17], v14, off offset:3584
	global_store_dword v[16:17], v15, off offset:3840
	s_cbranch_vccz .LBB0_699
	s_lshl_b32 s34, s65, 7
	v_mul_f32_e32 v0, 0x3fb8aa3b, v40
	v_mul_f32_e32 v1, 0x3fb8aa3b, v41
	s_ashr_i32 s35, s34, 31
	v_exp_f32_e32 v0, v0
	v_exp_f32_e32 v1, v1
	s_lshl_b64 s[34:35], s[34:35], 2
	s_add_u32 s34, s58, s34
	s_addc_u32 s35, s59, s35
	v_lshl_add_u64 v[2:3], v[34:35], 2, s[34:35]
	global_store_dwordx2 v[2:3], v[0:1], off
	s_branch .LBB0_699
